# NA bias-table copy loop: 4 dependent load-wait-write trips replaced by 4 loads in flight and one wait
# baseline (speedup 1.0000x reference)
; __device__ __forceinline__ void run_phase(Ctx& F0, const int p) {
;     ...
;         { float* rpb = (float*)(F.lds + MISC_OFF + 2048);
;           for (int i = F.tid; i < 4 * 15 * 31; i += NTHR) rpb[i] = inptr(F, 13)[(size_t)l * 4 * 15 * 31 + i];
;           __syncthreads();
.LBB0_774:
	s_movk_i32 s0, 0x744
	s_mov_b32 s40, 0x3e16c740
	v_cmp_gt_i32_e32 vcc, s0, v80
	s_and_saveexec_b64 s[0:1], vcc
	s_cbranch_execz .LBB0_777
	v_readlane_b32 s2, v255, 13
	v_mov_b32_e32 v0, s76
	ds_read2_b32 v[0:1], v0 offset0:26 offset1:27
	v_lshl_add_u32 v4, v80, 2, s2
	v_readlane_b32 s2, v255, 40
	v_readlane_b32 s3, v255, 41
	s_and_b64 s[2:3], s[2:3], exec
	s_cselect_b32 s2, 0x1d10, 0
	v_mov_b32_e32 v204, s2
	v_ashrrev_i32_e32 v81, 31, v80
	v_add_u32_e32 v5, 0xfffffe00, v80
	v_lshl_add_u64 v[2:3], v[80:81], 2, v[204:205]
	s_mov_b64 s[2:3], 0
	s_waitcnt lgkmcnt(0)
	v_readfirstlane_b32 s4, v0
	v_readfirstlane_b32 s5, v1
	s_nop 1
	v_lshl_add_u64 v[6:7], s[4:5], 0, v[2:3]
	v_lshl_add_u64 v[2:3], v[6:7], 0, s[68:69]
	v_lshl_add_u64 v[2:3], v[2:3], 0, s[68:69]
	global_load_dword v0, v[6:7], off
	global_load_dword v1, v[6:7], off offset:2048
	global_load_dword v5, v[2:3], off
	s_movk_i32 s4, 0x144
	v_cmp_gt_i32_e32 vcc, s4, v80
	s_and_saveexec_b64 s[2:3], vcc
	global_load_dword v6, v[2:3], off offset:2048
	s_or_b64 exec, exec, s[2:3]
	s_waitcnt vmcnt(0)
	ds_write_b32 v4, v0
	ds_write_b32 v4, v1 offset:2048
	ds_write_b32 v4, v5 offset:4096
	s_and_saveexec_b64 s[2:3], vcc
	ds_write_b32 v4, v6 offset:6144
